# grid barrier: the first workgroup to arrive on each XCD issues an early L2 write-back so the XCD leader's release fence has less to flush
# speedup vs baseline: 1.0105x; 1.0002x over previous
.LBB0_564:
	s_or_b64 exec, exec, s[14:15]
	v_cvt_f32_u32_e32 v4, v2
	s_waitcnt vmcnt(0)
	v_readfirstlane_b32 s4, v3
	v_sub_u32_e32 v3, 0, v2
	v_rcp_iflag_f32_e32 v4, v4
	v_add_u32_e32 v5, s4, v1
	v_mul_f32_e32 v4, 0x4f7ffffe, v4
	v_cvt_u32_f32_e32 v4, v4
	v_mul_lo_u32 v1, v3, v4
	v_mul_hi_u32 v1, v4, v1
	v_add_u32_e32 v1, v4, v1
	v_mul_hi_u32 v1, v5, v1
	v_mul_lo_u32 v3, v1, v2
	v_sub_u32_e32 v3, v5, v3
	v_add_u32_e32 v4, 1, v1
	v_cmp_ge_u32_e32 vcc, v3, v2
	s_nop 1
	v_cndmask_b32_e32 v1, v1, v4, vcc
	v_sub_u32_e32 v4, v3, v2
	v_cndmask_b32_e32 v3, v3, v4, vcc
	v_add_u32_e32 v4, 1, v1
	v_cmp_ge_u32_e32 vcc, v3, v2
	v_add_u32_e32 v3, 1, v5
	s_nop 0
	v_cndmask_b32_e32 v1, v1, v4, vcc
	v_mul_lo_u32 v4, v2, v1
	v_add_u32_e32 v2, v4, v2
	v_cmp_ne_u32_e32 vcc, v3, v2
	s_and_saveexec_b64 s[4:5], vcc
	s_xor_b64 s[4:5], exec, s[4:5]
	s_cbranch_execz .LBB0_578
	v_cmp_eq_u32_e32 vcc, v5, v4
	s_cbranch_vccz .Lxb_nofirst
	buffer_wbl2 sc1
.Lxb_nofirst:
	s_waitcnt lgkmcnt(0)
	global_load_dword v0, v237, s[12:13] offset:1024 sc1
	s_add_u32 s18, s12, 0x2400
	s_addc_u32 s19, s13, 0
	s_waitcnt vmcnt(0)
	v_cmp_eq_u32_e32 vcc, v0, v1
	s_and_saveexec_b64 s[14:15], vcc
	s_cbranch_execz .LBB0_577
	s_add_u32 s16, s90, 0x20200
	s_addc_u32 s17, s91, 0
	s_mov_b32 s6, 1
	s_mov_b64 s[30:31], 0
	s_branch .LBB0_568
